# attention phase: one static s_setprio 1 for waves 4-7, per-segment priority flips around PV deleted
# speedup vs baseline: 1.0126x; 1.0126x over previous
; __device__ __forceinline__ void prime(const BlockRef& cur, char* lds, Seam& S) {
;     const int tid = threadIdx.x, wid = __builtin_amdgcn_readfirstlane(tid >> 6), lane = tid & 63, r32 = lane & 31, hi = lane >> 5;
;     const int sr = tid >> 4, sc = (tid & 15) * 8, kws = KSWZ(sr, sc * 2); char* K_lds = lds + 2 * SHM_V;
; #pragma unroll
;     for (int d0 = 0; d0 < 8; ++d0) S.qr[d0] = load8<bf16>(cur.Q + (size_t)(wid * QBLK + r32) * PITCH + d0 * 16 + hi * 8);
;     SLOAD_H(cur.K, cur.V, 0); VMW(); SWRITE_HK(0);
;     __syncthreads();
; }
; __device__ __forceinline__ void block(const BlockRef& cur, const BlockRef& nxt, int skv, char* lds, Seam& S) {
;     const int W = 1 << 30;
;     const int tid = threadIdx.x, wid = __builtin_amdgcn_readfirstlane(tid >> 6), lane = tid & 63, r32 = lane & 31, hi = lane >> 5;
;     const int j_lo = 0;
;     int j_hi = (cur.P0 + QB - 1) / KVBLK + 1; if (j_hi > skv / KVBLK) j_hi = skv / KVBLK;
;     const int NT = j_hi - j_lo;
;     const int kbn = 0;
;     const int qlo = cur.P0 + wid * QBLK, qm = qlo + r32 - 4 * hi;
;     char* V_lds = lds; char* K_lds = lds + 2 * SHM_V;
;     float* ws = (float*)(lds + 2 * SHM_V + 2 * SHM_K) + wid * 64; float* li_l = ws, * al_l = ws + 32;
;     float m_reg = -1e30f, l_reg = 0; f32x16 o[4] = {};
;     const int sr = tid >> 4, sc = (tid & 15) * 8, vst0 = v_st(sr, sc), vst1 = v_st(32 + sr, sc), kws = KSWZ(sr, sc * 2);
;     const int vb0 = (int)(uintptr_t)V_lds + v_rd_base(lane);
; __global__ void __launch_bounds__(512, 2) fwd_mega(Params P_by_kernarg) {
;     ...
;           auto mk = [&](int L, int pass) { att::BlockRef r; const int vh = L >> 3, x = L & 7, qb = pass ? 15 - x : x, b = vh >> 5, h = (vh >> 2) & 7, c = (vh >> 1) & 1, vf = vh & 1;
;               r.Q = (const att::bf16*)(Qb + ((size_t)(b * TPAD + NMETA + qb * 256)) * 2048 + h * 256 + c * 128);
;               r.K = (const att::bf16*)(Kb + ((size_t)b * TPAD) * 2048 + h * 256 + c * 128);
;               r.V = (const att::bf16*)(Vb + ((size_t)b * TPAD) * 2048 + h * 256 + vf * 128);
;               r.O = (att::bf16*)(Opart + (size_t)c * MX * 2048 + ((size_t)(b * 4096 + qb * 256)) * 2048 + h * 256 + vf * 128);
;               r.P0 = NMETA + qb * 256; return r; };
;           int L = vcu;
;           if (L < 512) {
;               int pass = 0; att::BlockRef cur = mk(L, 0);
;               att::prime(cur, (char*)lds, S);
.LBB0_375:
	s_cmpk_lt_i32 s67, 0x200
	s_waitcnt lgkmcnt(0)
	s_barrier
	s_cbranch_scc0 .LBB0_543
	s_cmp_ge_u32 s66, 4
	s_cbranch_scc0 .Lattn_prio_done
	s_setprio 1
.Lattn_prio_done:
	s_ashr_i32 s4, s67, 8
	s_bfe_u32 s5, s67, 0x10004
	s_add_u32 s19, s34, 0x1d200000
	s_addc_u32 s21, s35, 0
	s_lshl_b32 s3, s67, 8
	s_mul_i32 s2, s4, 0x1080
	s_and_b32 s6, s3, 0x700
	s_add_i32 s2, s6, s2
	s_or_b32 s2, s2, 16
	s_ashr_i32 s3, s2, 31
	s_lshl_b64 s[2:3], s[2:3], 12
	s_add_u32 s2, s19, s2
	s_addc_u32 s3, s21, s3
	s_and_b32 s7, s68, 0x700
	s_lshl_b32 s7, s7, 1
	s_add_u32 s2, s2, s7
	s_addc_u32 s3, s3, 0
	s_lshl_b32 s12, s5, 8
	s_add_u32 s10, s2, s12
	s_addc_u32 s11, s3, 0
	s_add_u32 s39, s34, 0x1f300000
	s_addc_u32 s54, s35, 0
	s_mul_i32 s3, s4, 0x1080000
	s_mul_hi_i32 s2, s4, 0x1080000
	s_add_u32 s13, s39, s3
	s_addc_u32 s16, s54, s2
	s_add_u32 s13, s13, s7
	s_addc_u32 s16, s16, 0
	s_add_u32 s12, s13, s12
	s_addc_u32 s13, s16, 0
	s_add_u32 s55, s34, 0x21400000
	s_addc_u32 s56, s35, 0
	s_add_u32 s3, s55, s3
	s_addc_u32 s2, s56, s2
	s_add_u32 s3, s3, s7
	s_addc_u32 s2, s2, 0
	s_lshl_b32 s16, s67, 5
	s_and_b32 s36, s16, 0x100
	s_add_u32 s16, s3, s36
	s_addc_u32 s17, s2, 0
	s_add_u32 s57, s34, 0x30200000
	s_addc_u32 s58, s35, 0
	s_lshl_b32 s2, s5, 25
	s_add_u32 s5, s57, s2
	s_addc_u32 s34, s58, 0
	s_lshl_b32 s2, s4, 12
	s_or_b32 s2, s6, s2
	s_ashr_i32 s3, s2, 31
	s_lshl_b64 s[2:3], s[2:3], 12
	s_add_u32 s2, s5, s2
	s_addc_u32 s3, s34, s3
	s_add_u32 s2, s2, s7
	s_addc_u32 s3, s3, 0
	s_add_u32 s34, s2, s36
	v_readfirstlane_b32 s2, v1
	s_addc_u32 s35, s3, 0
	s_lshr_b32 s2, s2, 1
	s_and_b32 s2, s2, 0x7fffffe0
	s_waitcnt vmcnt(0)
	v_or_b32_e32 v2, s2, v198
	v_mov_b32_e32 v3, 0
	v_lshlrev_b64 v[4:5], 12, v[2:3]
	v_lshrrev_b32_e32 v2, 1, v1
	v_lshl_add_u64 v[4:5], s[10:11], 0, v[4:5]
	v_and_b32_e32 v2, 16, v2
	v_lshl_add_u64 v[12:13], v[4:5], 0, v[2:3]
	v_and_b32_e32 v14, 0x78, v167
	v_lshlrev_b32_e32 v2, 12, v197
	v_lshlrev_b32_e32 v16, 1, v14
	v_mov_b32_e32 v17, v3
	v_lshl_add_u64 v[4:5], s[12:13], 0, v[2:3]
	s_mov_b32 s2, 0x20000
	v_lshl_add_u64 v[18:19], v[4:5], 0, v[16:17]
	v_add_co_u32_e32 v20, vcc, s2, v18
	v_and_b32_e32 v26, 48, v16
	s_nop 0
	v_addc_co_u32_e32 v21, vcc, 0, v19, vcc
	global_load_dwordx4 v[4:7], v[18:19], off
	global_load_dwordx4 v[8:11], v[20:21], off
	global_load_dwordx4 v[160:163], v[12:13], off
	global_load_dwordx4 v[156:159], v[12:13], off offset:32
	global_load_dwordx4 v[152:155], v[12:13], off offset:64
	global_load_dwordx4 v[136:139], v[12:13], off offset:96
	global_load_dwordx4 v[140:143], v[12:13], off offset:128
	global_load_dwordx4 v[144:147], v[12:13], off offset:160
	global_load_dwordx4 v[148:151], v[12:13], off offset:192
	global_load_dwordx4 v[132:135], v[12:13], off offset:224
	v_lshl_add_u64 v[12:13], s[16:17], 0, v[2:3]
	v_lshl_add_u64 v[12:13], v[12:13], 0, v[16:17]
	v_add_co_u32_e32 v20, vcc, s2, v12
	v_and_b32_e32 v2, 48, v197
	s_nop 0
	v_addc_co_u32_e32 v21, vcc, 0, v13, vcc
	global_load_dwordx4 v[100:103], v[12:13], off
	global_load_dwordx4 v[104:107], v[20:21], off
	v_lshrrev_b32_e32 v12, 5, v1
	v_bfe_u32 v17, v1, 4, 2
	v_add_u32_e32 v20, 32, v197
	v_and_or_b32 v2, v164, 8, v2
	v_and_or_b32 v12, v12, 4, v17
	v_and_b32_e32 v17, 0x70, v20
	v_lshlrev_b32_e32 v23, 1, v20
	v_bfe_u32 v13, v167, 5, 2
	v_lshrrev_b32_e32 v2, 1, v2
	v_and_or_b32 v17, v23, 8, v17
	v_or_b32_e32 v2, v2, v13
	v_lshrrev_b32_e32 v17, 1, v17
	v_lshlrev_b32_e32 v12, 6, v12
	v_lshlrev_b32_e32 v2, 9, v2
	v_or_b32_e32 v13, v17, v13
	s_movk_i32 s3, 0x70
	v_lshlrev_b32_e32 v21, 4, v1
	v_lshlrev_b32_e32 v22, 1, v1
	v_or3_b32 v17, v2, v12, v26
	v_lshlrev_b32_e32 v2, 9, v13
	s_or_b32 s59, s6, 16
	v_lshlrev_b32_e32 v15, 8, v197
	v_and_b32_e32 v19, 0x70, v1
	v_and_b32_e32 v24, 0xc0, v21
	v_and_b32_e32 v22, 32, v22
	v_bitop3_b32 v25, v16, v1, s3 bitop3:0x78
	v_or3_b32 v12, v2, v12, v26
	v_and_b32_e32 v2, 0x118, v167
	s_cmp_lg_u32 0, -1
	v_bitop3_b32 v16, v16, v15, v19 bitop3:0xde
	v_add3_u32 v15, 0, v15, v25
	v_or3_b32 v2, v22, v24, v2
	s_cselect_b32 s2, 0, 0
	s_waitcnt vmcnt(0)
	v_add_u32_e32 v221, s2, v2
	v_and_b32_e32 v2, 0x70, v21
	v_lshlrev_b32_e32 v18, 11, v197
	s_mov_b32 s37, 0
	v_sub_u32_e32 v220, v198, v199
	v_cmp_gt_u32_e64 s[2:3], 32, v196
	v_lshlrev_b32_e32 v202, 14, v165
	v_mov_b32_e32 v203, v3
	v_lshlrev_b32_e32 v206, 1, v14
	s_brev_b32 s60, -3
	s_mov_b32 s61, 0x41000000
	s_mov_b32 s38, 0x3e0293ee
	s_waitcnt vmcnt(11)
	ds_write_b128 v15, v[4:7] offset:32768
	s_waitcnt vmcnt(10)
	ds_write_b128 v15, v[8:11] offset:40960
	v_or_b32_e32 v4, 32, v166
	v_xad_u32 v8, v4, v2, 0
	v_or_b32_e32 v4, 64, v166
	v_xad_u32 v9, v4, v2, 0
	v_or_b32_e32 v4, 0x60, v166
	v_xad_u32 v7, v166, v2, 0
	v_xad_u32 v10, v4, v2, 0
	v_or_b32_e32 v2, 0x20000, v18
	v_lshlrev_b32_e32 v5, 8, v198
	v_add_u32_e32 v4, 0x30000, v18
	v_lshlrev_b32_e32 v6, 11, v20
	v_and_b32_e32 v11, 1, v1
	v_lshlrev_b32_e32 v204, 1, v2
	v_mbcnt_lo_u32_b32 v2, -1, 0
	v_cmp_eq_u32_e64 s[4:5], 0, v11
	v_lshlrev_b32_e32 v208, 1, v4
	v_lshlrev_b32_e32 v210, 1, v18
	v_lshlrev_b32_e32 v212, 1, v6
	v_mbcnt_hi_u32_b32 v222, -1, v2
	v_lshlrev_b32_e32 v214, 1, v198
	v_add_u32_e32 v223, 0, v17
	v_add_u32_e32 v224, 0, v12
	v_add_u32_e32 v225, v7, v5
	v_add_u32_e32 v226, v8, v5
	v_add_u32_e32 v227, v9, v5
	v_add_u32_e32 v228, v10, v5
	v_mov_b32_e32 v229, 0xff800000
	v_mov_b32_e32 v230, 0xf149f2ca
	v_add_u32_e32 v231, 0, v16
	s_mov_b32 s63, 0
	s_mov_b32 s62, s67
	s_waitcnt lgkmcnt(0)
	s_barrier
	s_branch .LBB0_378

; __device__ __forceinline__ void finishSM(f32x16& p0, f32x16& p1, float alpha, float& l_reg, bf16x8& pa0, bf16x8& pa1, bf16x8& pa2, bf16x8& pa3) {
;     for (int r = 0; r < 16; ++r) p1[r] = __builtin_amdgcn_exp2f(p1[r]);
;     float ps;
;     {
;       float s0 = p0[0] + p1[0], s1 = p0[1] + p1[1], s2 = p0[2] + p1[2], s3 = p0[3] + p1[3];
; #pragma unroll
;       for (int r = 4; r < 16; r += 4) { s0 += p0[r]; s1 += p0[r + 1]; s2 += p0[r + 2]; s3 += p0[r + 3]; s0 += p1[r]; s1 += p1[r + 1]; s2 += p1[r + 2]; s3 += p1[r + 3]; }
;       ps = (s0 + s1) + (s2 + s3); }
;     { auto rr = __builtin_amdgcn_permlane32_swap(__float_as_uint(ps), __float_as_uint(ps), false, false);
;       ps = __uint_as_float(rr[0]) + __uint_as_float(rr[1]); }
;     l_reg = l_reg * alpha + ps;
;     ...
;     PK4(p0, 0, pa0); PK4(p0, 8, pa1); PK4(p1, 0, pa2); PK4(p1, 8, pa3);
;     ...
; }
; template <int KB, bool SK>
; __device__ __forceinline__ void qkt(f32x16& p0, f32x16& p1, const char* K_lds, int r32, int hi, const bf16x8* qr, bool act) {
;     if (SK && !act) { const float NEG = -__builtin_inff();
; #pragma unroll
;         for (int r = 0; r < 16; ++r) { p0[r] = NEG; p1[r] = NEG; } return; }
;     p0 = f32x16{}; p1 = f32x16{};
;     const char* kb[4];
; #pragma unroll
;     for (int dd = 0; dd < 4; ++dd) kb[dd] = K_lds + KB * SHM_K + KSWZ(r32, (dd * 16 + hi * 8) * 2);
; #pragma unroll
;     for (int d0 = 0; d0 < 8; ++d0) { const char* a = kb[d0 & 3] + (d0 >> 2) * 128;
;         bf16x8 b0 = *reinterpret_cast<const bf16x8*>(a);
;         bf16x8 b1 = *reinterpret_cast<const bf16x8*>(a + 32 * 256);
;         p0 = __builtin_amdgcn_mfma_f32_32x32x16_bf16(b0, qr[d0], p0, 0, 0, 0);
;         p1 = __builtin_amdgcn_mfma_f32_32x32x16_bf16(b1, qr[d0], p1, 0, 0, 0); }
.LBB0_383:
	ds_write_b128 v223, v[164:167] offset:16384
	ds_write_b128 v224, v[168:171] offset:16384
	ds_read_b128 v[68:71], v225 offset:49152
	ds_read_b128 v[100:103], v225 offset:49280
	v_exp_f32_e32 v2, v186
	v_exp_f32_e32 v186, v187
	v_exp_f32_e32 v184, v184
	s_waitcnt lgkmcnt(1)
	v_mfma_f32_32x32x16_bf16 v[84:99], v[68:71], v[160:163], 0
	ds_read_b128 v[68:71], v225 offset:57344
	ds_read_b128 v[104:107], v225 offset:57472
	ds_read_b128 v[108:111], v226 offset:49152
	ds_read_b128 v[112:115], v226 offset:49280
	v_exp_f32_e32 v185, v185
	v_exp_f32_e32 v178, v178
	v_exp_f32_e32 v179, v179
	v_exp_f32_e32 v176, v176
	v_exp_f32_e32 v177, v177
	s_waitcnt lgkmcnt(1)
	v_mfma_f32_32x32x16_bf16 v[84:99], v[108:111], v[156:159], v[84:99]
	ds_read_b128 v[108:111], v226 offset:57344
	ds_read_b128 v[164:167], v226 offset:57472
	ds_read_b128 v[168:171], v227 offset:49152
	ds_read_b128 v[190:193], v227 offset:49280
	ds_read_b128 v[234:237], v227 offset:57344
	ds_read_b128 v[238:241], v227 offset:57472
	v_exp_f32_e32 v174, v174
	v_exp_f32_e32 v175, v175
	v_exp_f32_e32 v172, v172
	v_exp_f32_e32 v173, v173
	s_sub_i32 s6, s74, 63
	v_mfma_f32_32x32x16_bf16 v[68:83], v[68:71], v[160:163], 0
	s_waitcnt lgkmcnt(5)
	v_mfma_f32_32x32x16_bf16 v[68:83], v[108:111], v[156:159], v[68:83]
	ds_read_b128 v[108:111], v228 offset:49152
	ds_read_b128 v[242:245], v228 offset:49280
	ds_read_b128 v[246:249], v228 offset:57344
	ds_read_b128 v[250:253], v228 offset:57472
	s_waitcnt lgkmcnt(7)
	v_mfma_f32_32x32x16_bf16 v[84:99], v[168:171], v[152:155], v[84:99]
	v_exp_f32_e32 v168, v182
	v_exp_f32_e32 v169, v183
	v_exp_f32_e32 v170, v180
	v_exp_f32_e32 v171, v181
	v_add_f32_e32 v180, v2, v129
	v_add_f32_e32 v181, v186, v131
	s_waitcnt lgkmcnt(5)
	v_mfma_f32_32x32x16_bf16 v[68:83], v[234:237], v[152:155], v[68:83]
	s_waitcnt lgkmcnt(3)
	v_mfma_f32_32x32x16_bf16 v[84:99], v[108:111], v[136:139], v[84:99]
	v_add_f32_e32 v108, v184, v128
	v_add_f32_e32 v109, v185, v130
	v_add_f32_e32 v110, v125, v180
	v_add_f32_e32 v111, v127, v181
	v_add_f32_e32 v108, v124, v108
	v_add_f32_e32 v109, v126, v109
	v_add_f32_e32 v110, v168, v110
	s_waitcnt lgkmcnt(1)
	v_mfma_f32_32x32x16_bf16 v[68:83], v[246:249], v[136:139], v[68:83]
	v_add_f32_e32 v111, v169, v111
	v_add_f32_e32 v108, v170, v108
	v_add_f32_e32 v109, v171, v109
	v_add_f32_e32 v110, v121, v110
	v_add_f32_e32 v111, v123, v111
	v_add_f32_e32 v108, v120, v108
	v_add_f32_e32 v109, v122, v109
	v_mfma_f32_32x32x16_bf16 v[84:99], v[100:103], v[140:143], v[84:99]
	v_add_f32_e32 v100, v178, v110
	v_add_f32_e32 v101, v179, v111
	v_add_f32_e32 v102, v176, v108
	v_add_f32_e32 v103, v177, v109
	v_add_f32_e32 v100, v117, v100
	v_add_f32_e32 v101, v119, v101
	v_add_f32_e32 v102, v116, v102
	v_mfma_f32_32x32x16_bf16 v[68:83], v[104:107], v[140:143], v[68:83]
	v_add_f32_e32 v103, v118, v103
	v_add_f32_e32 v100, v174, v100
	v_add_f32_e32 v101, v175, v101
	v_add_f32_e32 v102, v172, v102
	v_add_f32_e32 v103, v173, v103
	v_add_f32_e32 v100, v101, v100
	v_add_f32_e32 v101, v103, v102
	v_mfma_f32_32x32x16_bf16 v[84:99], v[112:115], v[144:147], v[84:99]
	v_add_f32_e32 v211, v101, v100
	v_mov_b32_e32 v213, v211
	s_nop 1
	v_permlane32_swap_b32_e32 v211, v213
	v_cvt_pk_bf16_f32 v100, v129, v131
	v_cvt_pk_bf16_f32 v101, v128, v130
	v_cvt_pk_bf16_f32 v102, v125, v127
	v_mfma_f32_32x32x16_bf16 v[68:83], v[164:167], v[144:147], v[68:83]
	v_cvt_pk_bf16_f32 v103, v124, v126
	v_cvt_pk_bf16_f32 v104, v121, v123
	v_cvt_pk_bf16_f32 v105, v120, v122
	v_cvt_pk_bf16_f32 v106, v117, v119
	v_cvt_pk_bf16_f32 v107, v116, v118
	v_cvt_pk_bf16_f32 v108, v2, v186
	v_cvt_pk_bf16_f32 v109, v184, v185
	v_mfma_f32_32x32x16_bf16 v[84:99], v[190:193], v[148:151], v[84:99]
	v_cvt_pk_bf16_f32 v110, v168, v169
	v_cvt_pk_bf16_f32 v111, v170, v171
	v_cvt_pk_bf16_f32 v112, v178, v179
	v_cvt_pk_bf16_f32 v113, v176, v177
	v_cvt_pk_bf16_f32 v114, v174, v175
	v_cvt_pk_bf16_f32 v115, v172, v173
	v_permlane32_swap_b32_e32 v100, v102
	v_mfma_f32_32x32x16_bf16 v[68:83], v[238:241], v[148:151], v[68:83]
	v_permlane32_swap_b32_e32 v101, v103
	v_permlane32_swap_b32_e32 v104, v106
	v_permlane32_swap_b32_e32 v105, v107
	v_permlane32_swap_b32_e32 v108, v110
	v_mfma_f32_32x32x16_bf16 v[84:99], v[242:245], v[132:135], v[84:99]
	v_permlane32_swap_b32_e32 v109, v111
	v_permlane32_swap_b32_e32 v112, v114
	v_permlane32_swap_b32_e32 v113, v115
	s_waitcnt lgkmcnt(0)
	v_mfma_f32_32x32x16_bf16 v[68:83], v[250:253], v[132:135], v[68:83]
	v_add_u32_e32 v236, s74, v197
	v_add_u32_e32 v2, 1, v236
	v_lshlrev_b64 v[116:117], 12, v[2:3]
	v_add_u32_e32 v2, 33, v236
	v_lshl_add_u64 v[118:119], v[216:217], 0, v[116:117]
	v_lshlrev_b64 v[120:121], 12, v[2:3]
	v_lshl_add_u64 v[116:117], v[218:219], 0, v[116:117]
	v_lshl_add_u64 v[122:123], v[216:217], 0, v[120:121]
	global_load_dwordx4 v[164:167], v[118:119], off
	global_load_dwordx4 v[168:171], v[122:123], off
	v_lshl_add_u64 v[118:119], v[218:219], 0, v[120:121]
	global_load_dwordx4 v[172:175], v[116:117], off
	global_load_dwordx4 v[176:179], v[118:119], off
	ds_read_b64_tr_b16 v[116:117], v221 offset:0
	ds_read_b64_tr_b16 v[118:119], v221 offset:0x800
	ds_read_b64_tr_b16 v[120:121], v221 offset:0x1000
	ds_read_b64_tr_b16 v[122:123], v221 offset:0x1800
	ds_read_b64_tr_b16 v[124:125], v221 offset:0x2000
	ds_read_b64_tr_b16 v[126:127], v221 offset:0x2800
	ds_read_b64_tr_b16 v[128:129], v221 offset:0x3000
	ds_read_b64_tr_b16 v[130:131], v221 offset:0x3800
	s_waitcnt lgkmcnt(0)
; __device__ __forceinline__ void mask_tile(f32x16& p0, f32x16& p1, int dq, unsigned W) {
;     const float NEG = -__builtin_inff();
; #pragma unroll
;     for (int r = 0; r < 16; ++r) {
;         const int c = (r & 3) + 8 * (r >> 2);
;         if ((unsigned)(dq - c) >= W) p0[r] = NEG;
;         if ((unsigned)(dq - c - 32) >= W) p1[r] = NEG;
;     }
; }
; template <int VB, bool SK>
; __device__ __forceinline__ void pv_tile(f32x16* o, int vb0, bf16x8 pa0, bf16x8 pa1, bf16x8 pa2, bf16x8 pa3, bool act) {
;     if (SK && !act) return;
;     ...
;     __builtin_amdgcn_s_setprio(1); PV_D0(0); PV_D0(1); PV_D0(2); PV_D0(3); __builtin_amdgcn_s_setprio(0);
	s_nop 0
	v_mfma_f32_32x32x16_bf16 v[52:67], v[100:103], v[116:119], v[52:67]
	ds_read_b64_tr_b16 v[116:117], v221 offset:0x200
	ds_read_b64_tr_b16 v[118:119], v221 offset:0xa00
	v_mfma_f32_32x32x16_bf16 v[52:67], v[104:107], v[120:123], v[52:67]
	ds_read_b64_tr_b16 v[120:121], v221 offset:0x1200
	ds_read_b64_tr_b16 v[122:123], v221 offset:0x1a00
	v_mfma_f32_32x32x16_bf16 v[52:67], v[108:111], v[124:127], v[52:67]
	ds_read_b64_tr_b16 v[124:125], v221 offset:0x2200
	ds_read_b64_tr_b16 v[126:127], v221 offset:0x2a00
	ds_read_b64_tr_b16 v[180:181], v221 offset:0x3200
	ds_read_b64_tr_b16 v[182:183], v221 offset:0x3a00
	s_waitcnt lgkmcnt(0)
	v_mfma_f32_32x32x16_bf16 v[52:67], v[112:115], v[128:131], v[52:67]
	v_mfma_f32_32x32x16_bf16 v[36:51], v[100:103], v[116:119], v[36:51]
	ds_read_b64_tr_b16 v[116:117], v221 offset:0x400
	ds_read_b64_tr_b16 v[118:119], v221 offset:0xc00
	v_mfma_f32_32x32x16_bf16 v[36:51], v[104:107], v[120:123], v[36:51]
	ds_read_b64_tr_b16 v[120:121], v221 offset:0x1400
	ds_read_b64_tr_b16 v[122:123], v221 offset:0x1c00
	v_mfma_f32_32x32x16_bf16 v[36:51], v[108:111], v[124:127], v[36:51]
	ds_read_b64_tr_b16 v[124:125], v221 offset:0x2400
	ds_read_b64_tr_b16 v[126:127], v221 offset:0x2c00
	ds_read_b64_tr_b16 v[128:129], v221 offset:0x3400
	ds_read_b64_tr_b16 v[130:131], v221 offset:0x3c00
	s_waitcnt lgkmcnt(0)
	v_mfma_f32_32x32x16_bf16 v[36:51], v[112:115], v[180:183], v[36:51]
	v_mfma_f32_32x32x16_bf16 v[20:35], v[100:103], v[116:119], v[20:35]
	ds_read_b64_tr_b16 v[116:117], v221 offset:0x600
	ds_read_b64_tr_b16 v[118:119], v221 offset:0xe00
	v_mfma_f32_32x32x16_bf16 v[20:35], v[104:107], v[120:123], v[20:35]
	ds_read_b64_tr_b16 v[120:121], v221 offset:0x1600
	ds_read_b64_tr_b16 v[122:123], v221 offset:0x1e00
	v_mfma_f32_32x32x16_bf16 v[20:35], v[108:111], v[124:127], v[20:35]
	ds_read_b64_tr_b16 v[124:125], v221 offset:0x2600
	ds_read_b64_tr_b16 v[126:127], v221 offset:0x2e00
	ds_read_b64_tr_b16 v[180:181], v221 offset:0x3600
	ds_read_b64_tr_b16 v[182:183], v221 offset:0x3e00
	s_waitcnt lgkmcnt(0)
	v_mfma_f32_32x32x16_bf16 v[20:35], v[112:115], v[128:131], v[20:35]
	v_mfma_f32_32x32x16_bf16 v[4:19], v[100:103], v[116:119], v[4:19]
	v_mfma_f32_32x32x16_bf16 v[4:19], v[104:107], v[120:123], v[4:19]
	v_mfma_f32_32x32x16_bf16 v[4:19], v[108:111], v[124:127], v[4:19]
	v_mfma_f32_32x32x16_bf16 v[4:19], v[112:115], v[180:183], v[4:19]
	s_cmp_le_i32 s74, s70
	s_cselect_b64 s[52:53], -1, 0
	s_cmp_gt_i32 s6, s71
	s_cselect_b64 s[6:7], -1, 0
	s_and_b64 s[6:7], s[6:7], s[52:53]
	s_and_b64 vcc, exec, s[6:7]
	v_add_u32_e32 v234, s59, v207
	s_cbranch_vccnz .LBB0_385
	v_subrev_u32_e32 v2, 64, v234
	v_cmp_gt_u32_e32 vcc, 2.0, v2
	v_add_u32_e32 v2, 0xbfffffa0, v234
	s_nop 0
	v_cndmask_b32_e32 v84, v229, v84, vcc
	v_cmp_lt_u32_e32 vcc, s60, v2
	v_add_u32_e32 v2, 0xbfffffbf, v234
	s_nop 0
	v_cndmask_b32_e32 v68, v229, v68, vcc
	v_cmp_lt_u32_e32 vcc, s60, v2
	v_add_u32_e32 v2, 0xbfffff9f, v234
	s_nop 0
	v_cndmask_b32_e32 v85, v229, v85, vcc
	v_cmp_lt_u32_e32 vcc, s60, v2
	v_add_u32_e32 v2, 0xbfffffbe, v234
	s_nop 0
	v_cndmask_b32_e32 v69, v229, v69, vcc
	v_cmp_lt_u32_e32 vcc, s60, v2
	v_add_u32_e32 v2, 0xbfffff9e, v234
	s_nop 0
	v_cndmask_b32_e32 v86, v229, v86, vcc
	v_cmp_lt_u32_e32 vcc, s60, v2
	v_add_u32_e32 v2, 0xbfffffbd, v234
	s_nop 0
	v_cndmask_b32_e32 v70, v229, v70, vcc
	v_cmp_lt_u32_e32 vcc, s60, v2
	v_add_u32_e32 v2, 0xbfffff9d, v234
	s_nop 0
	v_cndmask_b32_e32 v87, v229, v87, vcc
	v_cmp_lt_u32_e32 vcc, s60, v2
	v_add_u32_e32 v2, 0xbfffffb8, v234
	s_nop 0
	v_cndmask_b32_e32 v71, v229, v71, vcc
	v_cmp_lt_u32_e32 vcc, s60, v2
	v_add_u32_e32 v2, 0xbfffff98, v234
	s_nop 0
	v_cndmask_b32_e32 v88, v229, v88, vcc
	v_cmp_lt_u32_e32 vcc, s60, v2
	v_add_u32_e32 v2, 0xbfffffb7, v234
	s_nop 0
	v_cndmask_b32_e32 v72, v229, v72, vcc
	v_cmp_lt_u32_e32 vcc, s60, v2
	v_add_u32_e32 v2, 0xbfffff97, v234
	s_nop 0
	v_cndmask_b32_e32 v89, v229, v89, vcc
	v_cmp_lt_u32_e32 vcc, s60, v2
	v_add_u32_e32 v2, 0xbfffffb6, v234
	s_nop 0
	v_cndmask_b32_e32 v73, v229, v73, vcc
	v_cmp_lt_u32_e32 vcc, s60, v2
	v_add_u32_e32 v2, 0xbfffff96, v234
	s_nop 0
	v_cndmask_b32_e32 v90, v229, v90, vcc
	v_cmp_lt_u32_e32 vcc, s60, v2
	v_add_u32_e32 v2, 0xbfffffb5, v234
	s_nop 0
	v_cndmask_b32_e32 v74, v229, v74, vcc
	v_cmp_lt_u32_e32 vcc, s60, v2
	v_add_u32_e32 v2, 0xbfffff95, v234
	s_nop 0
	v_cndmask_b32_e32 v91, v229, v91, vcc
	v_cmp_lt_u32_e32 vcc, s60, v2
	v_add_u32_e32 v2, 0xbfffffb0, v234
	s_nop 0
	v_cndmask_b32_e32 v75, v229, v75, vcc
	v_cmp_lt_u32_e32 vcc, s60, v2
	v_add_u32_e32 v2, 0xbfffff90, v234
	s_nop 0
	v_cndmask_b32_e32 v92, v229, v92, vcc
	v_cmp_lt_u32_e32 vcc, s60, v2
	v_add_u32_e32 v2, 0xbfffffaf, v234
	s_nop 0
	v_cndmask_b32_e32 v76, v229, v76, vcc
	v_cmp_lt_u32_e32 vcc, s60, v2
	v_add_u32_e32 v2, 0xbfffff8f, v234
	s_nop 0
	v_cndmask_b32_e32 v93, v229, v93, vcc
	v_cmp_lt_u32_e32 vcc, s60, v2
	v_add_u32_e32 v2, 0xbfffffae, v234
	s_nop 0
	v_cndmask_b32_e32 v77, v229, v77, vcc
	v_cmp_lt_u32_e32 vcc, s60, v2
	v_add_u32_e32 v2, 0xbfffff8e, v234
	s_nop 0
	v_cndmask_b32_e32 v94, v229, v94, vcc
	v_cmp_lt_u32_e32 vcc, s60, v2
	v_add_u32_e32 v2, 0xbfffffad, v234
	s_nop 0
	v_cndmask_b32_e32 v78, v229, v78, vcc
	v_cmp_lt_u32_e32 vcc, s60, v2
	v_add_u32_e32 v2, 0xbfffff8d, v234
	s_nop 0
	v_cndmask_b32_e32 v95, v229, v95, vcc
	v_cmp_lt_u32_e32 vcc, s60, v2
	v_add_u32_e32 v2, 0xbfffffa8, v234
	s_nop 0
	v_cndmask_b32_e32 v79, v229, v79, vcc
	v_cmp_lt_u32_e32 vcc, s60, v2
	v_add_u32_e32 v2, 0xbfffff88, v234
	s_nop 0
	v_cndmask_b32_e32 v96, v229, v96, vcc
	v_cmp_lt_u32_e32 vcc, s60, v2
	v_add_u32_e32 v2, 0xbfffffa7, v234
	s_nop 0
	v_cndmask_b32_e32 v80, v229, v80, vcc
	v_cmp_lt_u32_e32 vcc, s60, v2
	v_add_u32_e32 v2, 0xbfffff87, v234
	s_nop 0
	v_cndmask_b32_e32 v97, v229, v97, vcc
	v_cmp_lt_u32_e32 vcc, s60, v2
	v_add_u32_e32 v2, 0xbfffffa6, v234
	s_nop 0
	v_cndmask_b32_e32 v81, v229, v81, vcc
	v_cmp_lt_u32_e32 vcc, s60, v2
	v_add_u32_e32 v2, 0xbfffff86, v234
	s_nop 0
	v_cndmask_b32_e32 v98, v229, v98, vcc
	v_cmp_lt_u32_e32 vcc, s60, v2
	v_add_u32_e32 v2, 0xbfffffa5, v234
	s_nop 0
	v_cndmask_b32_e32 v82, v229, v82, vcc
	v_cmp_lt_u32_e32 vcc, s60, v2
	v_add_u32_e32 v2, 0xbfffff85, v234
	s_nop 0
	v_cndmask_b32_e32 v99, v229, v99, vcc
	v_cmp_lt_u32_e32 vcc, s60, v2
	s_nop 1
	v_cndmask_b32_e32 v83, v229, v83, vcc

; __device__ __forceinline__ void mask_tile(f32x16& p0, f32x16& p1, int dq, unsigned W) {
;     const float NEG = -__builtin_inff();
; #pragma unroll
;     for (int r = 0; r < 16; ++r) {
;         const int c = (r & 3) + 8 * (r >> 2);
;         if ((unsigned)(dq - c) >= W) p0[r] = NEG;
;         if ((unsigned)(dq - c - 32) >= W) p1[r] = NEG;
;     }
; }
; template <int VB, bool SK>
; __device__ __forceinline__ void pv_tile(f32x16* o, int vb0, bf16x8 pa0, bf16x8 pa1, bf16x8 pa2, bf16x8 pa3, bool act) {
;     if (SK && !act) return;
;     ...
;     __builtin_amdgcn_s_setprio(1); PV_D0(0); PV_D0(1); PV_D0(2); PV_D0(3); __builtin_amdgcn_s_setprio(0);
.LBB0_391:
	s_add_i32 s6, s74, 64
	s_add_i32 s75, s74, 1
	ds_read_b64_tr_b16 v[240:241], v221 offset:0x4000
	ds_read_b64_tr_b16 v[242:243], v221 offset:0x4800
	ds_read_b64_tr_b16 v[244:245], v221 offset:0x5000
	ds_read_b64_tr_b16 v[246:247], v221 offset:0x5800
	ds_read_b64_tr_b16 v[248:249], v221 offset:0x6000
	ds_read_b64_tr_b16 v[250:251], v221 offset:0x6800
	ds_read_b64_tr_b16 v[252:253], v221 offset:0x7000
	ds_read_b64_tr_b16 v[254:255], v221 offset:0x7800
	s_waitcnt lgkmcnt(0)
	s_nop 0
	v_mfma_f32_32x32x16_bf16 v[52:67], v[180:183], v[240:243], v[52:67]
	ds_read_b64_tr_b16 v[240:241], v221 offset:0x4200
	ds_read_b64_tr_b16 v[242:243], v221 offset:0x4a00
	v_mfma_f32_32x32x16_bf16 v[52:67], v[184:187], v[244:247], v[52:67]
	ds_read_b64_tr_b16 v[244:245], v221 offset:0x5200
	ds_read_b64_tr_b16 v[246:247], v221 offset:0x5a00
	v_mfma_f32_32x32x16_bf16 v[52:67], v[188:191], v[248:251], v[52:67]
	ds_read_b64_tr_b16 v[248:249], v221 offset:0x6200
	ds_read_b64_tr_b16 v[250:251], v221 offset:0x6a00
	v_mfma_f32_32x32x16_bf16 v[52:67], v[192:195], v[252:255], v[52:67]
	ds_read_b64_tr_b16 v[252:253], v221 offset:0x7200
	ds_read_b64_tr_b16 v[254:255], v221 offset:0x7a00
	s_waitcnt lgkmcnt(0)
	v_mfma_f32_32x32x16_bf16 v[36:51], v[180:183], v[240:243], v[36:51]
	ds_read_b64_tr_b16 v[240:241], v221 offset:0x4400
	ds_read_b64_tr_b16 v[242:243], v221 offset:0x4c00
	v_mfma_f32_32x32x16_bf16 v[36:51], v[184:187], v[244:247], v[36:51]
	ds_read_b64_tr_b16 v[244:245], v221 offset:0x5400
	ds_read_b64_tr_b16 v[246:247], v221 offset:0x5c00
	v_mfma_f32_32x32x16_bf16 v[36:51], v[188:191], v[248:251], v[36:51]
	ds_read_b64_tr_b16 v[248:249], v221 offset:0x6400
	ds_read_b64_tr_b16 v[250:251], v221 offset:0x6c00
	v_mfma_f32_32x32x16_bf16 v[36:51], v[192:195], v[252:255], v[36:51]
	ds_read_b64_tr_b16 v[252:253], v221 offset:0x7400
	ds_read_b64_tr_b16 v[254:255], v221 offset:0x7c00
	s_waitcnt lgkmcnt(0)
	v_mfma_f32_32x32x16_bf16 v[20:35], v[180:183], v[240:243], v[20:35]
	ds_read_b64_tr_b16 v[240:241], v221 offset:0x4600
	ds_read_b64_tr_b16 v[242:243], v221 offset:0x4e00
	v_mfma_f32_32x32x16_bf16 v[20:35], v[184:187], v[244:247], v[20:35]
	ds_read_b64_tr_b16 v[244:245], v221 offset:0x5600
	ds_read_b64_tr_b16 v[246:247], v221 offset:0x5e00
	v_mfma_f32_32x32x16_bf16 v[20:35], v[188:191], v[248:251], v[20:35]
	ds_read_b64_tr_b16 v[248:249], v221 offset:0x6600
	ds_read_b64_tr_b16 v[250:251], v221 offset:0x6e00
	v_mfma_f32_32x32x16_bf16 v[20:35], v[192:195], v[252:255], v[20:35]
	ds_read_b64_tr_b16 v[252:253], v221 offset:0x7600
	ds_read_b64_tr_b16 v[254:255], v221 offset:0x7e00
	s_waitcnt lgkmcnt(0)
	v_mfma_f32_32x32x16_bf16 v[4:19], v[180:183], v[240:243], v[4:19]
	v_mfma_f32_32x32x16_bf16 v[4:19], v[184:187], v[244:247], v[4:19]
	v_mfma_f32_32x32x16_bf16 v[4:19], v[188:191], v[248:251], v[4:19]
	v_mfma_f32_32x32x16_bf16 v[4:19], v[192:195], v[252:255], v[4:19]
	s_cmp_le_i32 s6, s70
	s_cselect_b64 s[6:7], -1, 0
	s_cmp_gt_i32 s75, s71
	s_cselect_b64 s[76:77], -1, 0
	s_and_b64 s[6:7], s[76:77], s[6:7]
	s_and_b64 vcc, exec, s[6:7]
	s_cbranch_vccnz .LBB0_393
	v_add_u32_e32 v2, 0xffffff80, v234
	v_cmp_gt_u32_e32 vcc, 2.0, v2
	v_add_u32_e32 v2, 0xbfffff60, v234
	s_nop 0
	v_cndmask_b32_e32 v116, v229, v116, vcc
	v_cmp_lt_u32_e32 vcc, s60, v2
	v_add_u32_e32 v2, 0xbfffff7f, v234
	s_nop 0
	v_cndmask_b32_e32 v100, v229, v100, vcc
	v_cmp_lt_u32_e32 vcc, s60, v2
	v_add_u32_e32 v2, 0xbfffff5f, v234
	s_nop 0
	v_cndmask_b32_e32 v117, v229, v117, vcc
	v_cmp_lt_u32_e32 vcc, s60, v2
	v_add_u32_e32 v2, 0xbfffff7e, v234
	s_nop 0
	v_cndmask_b32_e32 v101, v229, v101, vcc
	v_cmp_lt_u32_e32 vcc, s60, v2
	v_add_u32_e32 v2, 0xbfffff5e, v234
	s_nop 0
	v_cndmask_b32_e32 v118, v229, v118, vcc
	v_cmp_lt_u32_e32 vcc, s60, v2
	v_add_u32_e32 v2, 0xbfffff7d, v234
	s_nop 0
	v_cndmask_b32_e32 v102, v229, v102, vcc
	v_cmp_lt_u32_e32 vcc, s60, v2
	v_add_u32_e32 v2, 0xbfffff5d, v234
	s_nop 0
	v_cndmask_b32_e32 v119, v229, v119, vcc
	v_cmp_lt_u32_e32 vcc, s60, v2
	v_add_u32_e32 v2, 0xbfffff78, v234
	s_nop 0
	v_cndmask_b32_e32 v103, v229, v103, vcc
	v_cmp_lt_u32_e32 vcc, s60, v2
	v_add_u32_e32 v2, 0xbfffff58, v234
	s_nop 0
	v_cndmask_b32_e32 v120, v229, v120, vcc
	v_cmp_lt_u32_e32 vcc, s60, v2
	v_add_u32_e32 v2, 0xbfffff77, v234
	s_nop 0
	v_cndmask_b32_e32 v104, v229, v104, vcc
	v_cmp_lt_u32_e32 vcc, s60, v2
	v_add_u32_e32 v2, 0xbfffff57, v234
	s_nop 0
	v_cndmask_b32_e32 v121, v229, v121, vcc
	v_cmp_lt_u32_e32 vcc, s60, v2
	v_add_u32_e32 v2, 0xbfffff76, v234
	s_nop 0
	v_cndmask_b32_e32 v105, v229, v105, vcc
	v_cmp_lt_u32_e32 vcc, s60, v2
	v_add_u32_e32 v2, 0xbfffff56, v234
	s_nop 0
	v_cndmask_b32_e32 v122, v229, v122, vcc
	v_cmp_lt_u32_e32 vcc, s60, v2
	v_add_u32_e32 v2, 0xbfffff75, v234
	s_nop 0
	v_cndmask_b32_e32 v106, v229, v106, vcc
	v_cmp_lt_u32_e32 vcc, s60, v2
	v_add_u32_e32 v2, 0xbfffff55, v234
	s_nop 0
	v_cndmask_b32_e32 v123, v229, v123, vcc
	v_cmp_lt_u32_e32 vcc, s60, v2
	v_add_u32_e32 v2, 0xbfffff70, v234
	s_nop 0
	v_cndmask_b32_e32 v107, v229, v107, vcc
	v_cmp_lt_u32_e32 vcc, s60, v2
	v_add_u32_e32 v2, 0xbfffff50, v234
	s_nop 0
	v_cndmask_b32_e32 v124, v229, v124, vcc
	v_cmp_lt_u32_e32 vcc, s60, v2
	v_add_u32_e32 v2, 0xbfffff6f, v234
	s_nop 0
	v_cndmask_b32_e32 v108, v229, v108, vcc
	v_cmp_lt_u32_e32 vcc, s60, v2
	v_add_u32_e32 v2, 0xbfffff4f, v234
	s_nop 0
	v_cndmask_b32_e32 v125, v229, v125, vcc
	v_cmp_lt_u32_e32 vcc, s60, v2
	v_add_u32_e32 v2, 0xbfffff6e, v234
	s_nop 0
	v_cndmask_b32_e32 v109, v229, v109, vcc
	v_cmp_lt_u32_e32 vcc, s60, v2
	v_add_u32_e32 v2, 0xbfffff4e, v234
	s_nop 0
	v_cndmask_b32_e32 v126, v229, v126, vcc
	v_cmp_lt_u32_e32 vcc, s60, v2
	v_add_u32_e32 v2, 0xbfffff6d, v234
	s_nop 0
	v_cndmask_b32_e32 v110, v229, v110, vcc
	v_cmp_lt_u32_e32 vcc, s60, v2
	v_add_u32_e32 v2, 0xbfffff4d, v234
	s_nop 0
	v_cndmask_b32_e32 v127, v229, v127, vcc
	v_cmp_lt_u32_e32 vcc, s60, v2
	v_add_u32_e32 v2, 0xbfffff68, v234
	s_nop 0
	v_cndmask_b32_e32 v111, v229, v111, vcc
	v_cmp_lt_u32_e32 vcc, s60, v2
	v_add_u32_e32 v2, 0xbfffff48, v234
	s_nop 0
	v_cndmask_b32_e32 v128, v229, v128, vcc
	v_cmp_lt_u32_e32 vcc, s60, v2
	v_add_u32_e32 v2, 0xbfffff67, v234
	s_nop 0
	v_cndmask_b32_e32 v112, v229, v112, vcc
	v_cmp_lt_u32_e32 vcc, s60, v2
	v_add_u32_e32 v2, 0xbfffff47, v234
	s_nop 0
	v_cndmask_b32_e32 v129, v229, v129, vcc
	v_cmp_lt_u32_e32 vcc, s60, v2
	v_add_u32_e32 v2, 0xbfffff66, v234
	s_nop 0
	v_cndmask_b32_e32 v113, v229, v113, vcc
	v_cmp_lt_u32_e32 vcc, s60, v2
	v_add_u32_e32 v2, 0xbfffff46, v234
	s_nop 0
	v_cndmask_b32_e32 v130, v229, v130, vcc
	v_cmp_lt_u32_e32 vcc, s60, v2
	v_add_u32_e32 v2, 0xbfffff65, v234
	s_nop 0
	v_cndmask_b32_e32 v114, v229, v114, vcc
	v_cmp_lt_u32_e32 vcc, s60, v2
	v_add_u32_e32 v2, 0xbfffff45, v234
	s_nop 0
	v_cndmask_b32_e32 v131, v229, v131, vcc
	v_cmp_lt_u32_e32 vcc, s60, v2
	s_nop 1
	v_cndmask_b32_e32 v115, v229, v115, vcc

; #define SBAR() __builtin_amdgcn_sched_barrier(0)
; #define SLOAD_H(Kp, Vp, k0) do { S.st_v0 = load8<bf16>(ROW(Vp, k0, sr)); S.st_v1 = load8<bf16>(ROW(Vp, k0, 32 + sr));              \
;                          S.st_k0 = load8<bf16>(ROW(Kp, k0, sr)); S.st_k1 = load8<bf16>(ROW(Kp, k0, 32 + sr)); } while (0)
; #define ACT(t) (KBASE(t) <= qlo + QBLK - 1 && KBASE(t) + KVBLK - 1 >= qlo - W + 1)
; __device__ __forceinline__ void finishSM(f32x16& p0, f32x16& p1, float alpha, float& l_reg, bf16x8& pa0, bf16x8& pa1, bf16x8& pa2, bf16x8& pa3) {
;     for (int r = 0; r < 16; ++r) p1[r] = __builtin_amdgcn_exp2f(p1[r]);
;     float ps;
;     {
;       float s0 = p0[0] + p1[0], s1 = p0[1] + p1[1], s2 = p0[2] + p1[2], s3 = p0[3] + p1[3];
; #pragma unroll
;       for (int r = 4; r < 16; r += 4) { s0 += p0[r]; s1 += p0[r + 1]; s2 += p0[r + 2]; s3 += p0[r + 3]; s0 += p1[r]; s1 += p1[r + 1]; s2 += p1[r + 2]; s3 += p1[r + 3]; }
;       ps = (s0 + s1) + (s2 + s3); }
;     { auto rr = __builtin_amdgcn_permlane32_swap(__float_as_uint(ps), __float_as_uint(ps), false, false);
;       ps = __uint_as_float(rr[0]) + __uint_as_float(rr[1]); }
;     l_reg = l_reg * alpha + ps;
;     ...
;     PK4(p0, 0, pa0); PK4(p0, 8, pa1); PK4(p1, 0, pa2); PK4(p1, 8, pa3);
; __device__ __forceinline__ void block(const BlockRef& cur, const BlockRef& nxt, int skv, char* lds, Seam& S) {
;     ...
;     SLOAD_H(nxt.K, nxt.V, kbn); SBAR();
; #pragma unroll
;     for (int d0 = 0; d0 < 8; ++d0) S.qr[d0] = load8<bf16>(nxt.Q + (size_t)(wid * QBLK + r32) * PITCH + d0 * 16 + hi * 8);
;     SBAR();
;     finishSM(pA0, pA1, alA, l_reg, pa0, pa1, pa2, pa3); SBAR();
;     pv_tile<0, SK>(o, vb0, pa0, pa1, pa2, pa3, ACT(even ? NT - 2 : NT - 1));
.LBB0_403:
	v_mov_b32_e32 v211, v3
	v_mov_b32_e32 v213, v3
	v_lshl_add_u64 v[100:101], s[48:49], 0, v[210:211]
	v_mov_b32_e32 v207, v3
	v_lshl_add_u64 v[102:103], s[48:49], 0, v[212:213]
	v_lshl_add_u64 v[108:109], s[46:47], 0, v[210:211]
	v_lshl_add_u64 v[110:111], s[46:47], 0, v[212:213]
	v_lshl_add_u64 v[100:101], v[100:101], 0, v[206:207]
	v_lshl_add_u64 v[104:105], v[102:103], 0, v[206:207]
	v_lshl_add_u64 v[108:109], v[108:109], 0, v[206:207]
	v_lshl_add_u64 v[112:113], v[110:111], 0, v[206:207]
	global_load_dwordx4 v[100:103], v[100:101], off
	s_nop 0
	global_load_dwordx4 v[104:107], v[104:105], off
	s_nop 0
	global_load_dwordx4 v[108:111], v[108:109], off
	s_nop 0
	global_load_dwordx4 v[112:115], v[112:113], off
	v_or_b32_e32 v2, s36, v198
	v_lshlrev_b64 v[132:133], 12, v[2:3]
	v_lshl_add_u64 v[132:133], s[44:45], 0, v[132:133]
	v_mov_b32_e32 v201, v3
	v_lshl_add_u64 v[132:133], v[132:133], 0, v[200:201]
	global_load_dwordx4 v[160:163], v[132:133], off
	global_load_dwordx4 v[156:159], v[132:133], off offset:32
	global_load_dwordx4 v[152:155], v[132:133], off offset:64
	global_load_dwordx4 v[136:139], v[132:133], off offset:96
	global_load_dwordx4 v[140:143], v[132:133], off offset:128
	global_load_dwordx4 v[144:147], v[132:133], off offset:160
	global_load_dwordx4 v[148:151], v[132:133], off offset:192
	s_nop 0
	global_load_dwordx4 v[132:135], v[132:133], off offset:224
	v_exp_f32_e32 v169, v186
	v_exp_f32_e32 v171, v187
	v_exp_f32_e32 v168, v184
	v_exp_f32_e32 v170, v185
	v_exp_f32_e32 v185, v182
	v_exp_f32_e32 v183, v183
	v_exp_f32_e32 v184, v180
	v_exp_f32_e32 v182, v181
	v_exp_f32_e32 v181, v178
	v_exp_f32_e32 v179, v179
	v_exp_f32_e32 v180, v176
	v_exp_f32_e32 v178, v177
	v_pk_add_f32 v[164:165], v[128:129], v[168:169]
	v_pk_add_f32 v[166:167], v[130:131], v[170:171]
	v_pk_add_f32 v[164:165], v[124:125], v[164:165]
	v_pk_add_f32 v[166:167], v[126:127], v[166:167]
	v_exp_f32_e32 v177, v174
	v_exp_f32_e32 v175, v175
	v_exp_f32_e32 v176, v172
	v_exp_f32_e32 v174, v173
	v_pk_add_f32 v[164:165], v[184:185], v[164:165]
	v_pk_add_f32 v[166:167], v[182:183], v[166:167]
	v_pk_add_f32 v[164:165], v[120:121], v[164:165]
	v_pk_add_f32 v[166:167], v[122:123], v[166:167]
	v_pk_add_f32 v[164:165], v[180:181], v[164:165]
	v_pk_add_f32 v[166:167], v[178:179], v[166:167]
	v_pk_add_f32 v[164:165], v[116:117], v[164:165]
	v_pk_add_f32 v[166:167], v[118:119], v[166:167]
	v_pk_add_f32 v[164:165], v[176:177], v[164:165]
	v_pk_add_f32 v[166:167], v[174:175], v[166:167]
	s_nop 0
	v_pk_add_f32 v[164:165], v[166:167], v[164:165]
	s_nop 0
	v_pk_add_f32 v[164:165], v[164:165], v[164:165] op_sel:[0,1] op_sel_hi:[1,0]
	s_nop 0
	v_mov_b32_e32 v2, v164
	s_nop 1
	v_permlane32_swap_b32_e32 v164, v2
	v_add_f32_e32 v2, v164, v2
	v_fmac_f32_e32 v2, v232, v189
	v_cvt_pk_bf16_f32 v164, v129, v131
	v_cvt_pk_bf16_f32 v165, v128, v130
	v_cvt_pk_bf16_f32 v166, v125, v127
	v_cvt_pk_bf16_f32 v167, v124, v126
	v_cvt_pk_bf16_f32 v124, v121, v123
	v_cvt_pk_bf16_f32 v125, v120, v122
	v_cvt_pk_bf16_f32 v126, v117, v119
	v_cvt_pk_bf16_f32 v127, v116, v118
	v_cvt_pk_bf16_f32 v116, v169, v171
	v_cvt_pk_bf16_f32 v117, v168, v170
	v_cvt_pk_bf16_f32 v118, v185, v183
	v_cvt_pk_bf16_f32 v119, v184, v182
	v_cvt_pk_bf16_f32 v120, v181, v179
	v_cvt_pk_bf16_f32 v121, v180, v178
	v_cvt_pk_bf16_f32 v122, v177, v175
	v_cvt_pk_bf16_f32 v123, v176, v174
	s_nop 0
	v_permlane32_swap_b32_e32 v164, v166
	v_permlane32_swap_b32_e32 v165, v167
	v_permlane32_swap_b32_e32 v124, v126
	v_permlane32_swap_b32_e32 v125, v127
	v_permlane32_swap_b32_e32 v116, v118
	v_permlane32_swap_b32_e32 v117, v119
	v_permlane32_swap_b32_e32 v120, v122
	v_permlane32_swap_b32_e32 v121, v123
	ds_read_b64_tr_b16 v[128:129], v221 offset:0
	ds_read_b64_tr_b16 v[130:131], v221 offset:0x800
	ds_read_b64_tr_b16 v[168:169], v221 offset:0x1000
	ds_read_b64_tr_b16 v[170:171], v221 offset:0x1800
	ds_read_b64_tr_b16 v[172:173], v221 offset:0x2000
	ds_read_b64_tr_b16 v[174:175], v221 offset:0x2800
	ds_read_b64_tr_b16 v[176:177], v221 offset:0x3000
	ds_read_b64_tr_b16 v[178:179], v221 offset:0x3800
	s_waitcnt lgkmcnt(0)
	s_nop 0
	v_mfma_f32_32x32x16_bf16 v[52:67], v[164:167], v[128:131], v[52:67]
	ds_read_b64_tr_b16 v[128:129], v221 offset:0x200
	ds_read_b64_tr_b16 v[130:131], v221 offset:0xa00
	v_mfma_f32_32x32x16_bf16 v[52:67], v[124:127], v[168:171], v[52:67]
	ds_read_b64_tr_b16 v[168:169], v221 offset:0x1200
	ds_read_b64_tr_b16 v[170:171], v221 offset:0x1a00
	v_mfma_f32_32x32x16_bf16 v[52:67], v[116:119], v[172:175], v[52:67]
	ds_read_b64_tr_b16 v[172:173], v221 offset:0x2200
	ds_read_b64_tr_b16 v[174:175], v221 offset:0x2a00
	ds_read_b64_tr_b16 v[180:181], v221 offset:0x3200
	ds_read_b64_tr_b16 v[182:183], v221 offset:0x3a00
	s_waitcnt lgkmcnt(0)
	v_mfma_f32_32x32x16_bf16 v[52:67], v[120:123], v[176:179], v[52:67]
	v_mfma_f32_32x32x16_bf16 v[36:51], v[164:167], v[128:131], v[36:51]
	ds_read_b64_tr_b16 v[128:129], v221 offset:0x400
	ds_read_b64_tr_b16 v[130:131], v221 offset:0xc00
	v_mfma_f32_32x32x16_bf16 v[36:51], v[124:127], v[168:171], v[36:51]
	ds_read_b64_tr_b16 v[168:169], v221 offset:0x1400
	ds_read_b64_tr_b16 v[170:171], v221 offset:0x1c00
	v_mfma_f32_32x32x16_bf16 v[36:51], v[116:119], v[172:175], v[36:51]
	ds_read_b64_tr_b16 v[172:173], v221 offset:0x2400
	ds_read_b64_tr_b16 v[174:175], v221 offset:0x2c00
	ds_read_b64_tr_b16 v[176:177], v221 offset:0x3400
	ds_read_b64_tr_b16 v[178:179], v221 offset:0x3c00
	s_waitcnt lgkmcnt(0)
	v_mfma_f32_32x32x16_bf16 v[36:51], v[120:123], v[180:183], v[36:51]
	v_mfma_f32_32x32x16_bf16 v[20:35], v[164:167], v[128:131], v[20:35]
	ds_read_b64_tr_b16 v[128:129], v221 offset:0x600
	ds_read_b64_tr_b16 v[130:131], v221 offset:0xe00
	v_mfma_f32_32x32x16_bf16 v[20:35], v[124:127], v[168:171], v[20:35]
	ds_read_b64_tr_b16 v[168:169], v221 offset:0x1600
	ds_read_b64_tr_b16 v[170:171], v221 offset:0x1e00
	v_mfma_f32_32x32x16_bf16 v[20:35], v[116:119], v[172:175], v[20:35]
	ds_read_b64_tr_b16 v[172:173], v221 offset:0x2600
	ds_read_b64_tr_b16 v[174:175], v221 offset:0x2e00
	ds_read_b64_tr_b16 v[180:181], v221 offset:0x3600
	ds_read_b64_tr_b16 v[182:183], v221 offset:0x3e00
	s_waitcnt lgkmcnt(0)
	v_mfma_f32_32x32x16_bf16 v[20:35], v[120:123], v[176:179], v[20:35]
	v_mfma_f32_32x32x16_bf16 v[4:19], v[164:167], v[128:131], v[4:19]
	v_mfma_f32_32x32x16_bf16 v[4:19], v[124:127], v[168:171], v[4:19]
	v_mfma_f32_32x32x16_bf16 v[4:19], v[116:119], v[172:175], v[4:19]
	v_mfma_f32_32x32x16_bf16 v[4:19], v[120:123], v[180:183], v[4:19]
	s_andn2_b64 vcc, exec, s[6:7]
	s_cbranch_vccnz .LBB0_411
; #define RESC(a) do { if (__any((a) < 1.f)) { if (hi == 0) al_l[r32] = (a); asm volatile("s_waitcnt lgkmcnt(0)" ::: "memory");              \
;                      for (int d_ = 0; d_ < 4; ++d_) for (int r = 0; r < 16; ++r) o[d_][r] *= al_l[crow(r, hi)]; } } while (0)
; #define MASKT(P0_, P1_, t) do { const int kb_ = KBASE(t); if ((!SK || ACT(t)) && (kb_ + KVBLK - 1 > qlo || kb_ <= qlo + QBLK - 1 - W)) mask_tile(P0_, P1_, qm - kb_, (unsigned)W); } while (0)
; __device__ __forceinline__ void mask_tile(f32x16& p0, f32x16& p1, int dq, unsigned W) {
;     const float NEG = -__builtin_inff();
; #pragma unroll
;     for (int r = 0; r < 16; ++r) {
;         const int c = (r & 3) + 8 * (r >> 2);
;         if ((unsigned)(dq - c) >= W) p0[r] = NEG;
;         if ((unsigned)(dq - c - 32) >= W) p1[r] = NEG;
;     }
; }
; __device__ __forceinline__ void block(const BlockRef& cur, const BlockRef& nxt, int skv, char* lds, Seam& S) {
;     ...
;     if (even) { MASKT(pB0, pB1, NT - 1); partialSM(pB0, pB1, m_reg, mnB, alB); __syncthreads(); RESC(alB);
	s_lshl_b32 s7, s72, 6
	s_sub_i32 s6, s7, 64
	s_add_i32 s7, s7, -1
	s_cmp_le_i32 s7, s70
	s_cselect_b64 s[52:53], -1, 0
	s_cmp_gt_i32 s6, s71
	s_cselect_b64 s[70:71], -1, 0
	s_and_b64 s[52:53], s[52:53], s[70:71]
	s_and_b64 vcc, exec, s[52:53]
	s_cbranch_vccnz .LBB0_406
	v_subrev_u32_e32 v116, s6, v215
	v_cmp_gt_u32_e32 vcc, 2.0, v116
	v_add_u32_e32 v117, 0xbfffffe0, v116
	s_nop 0
	v_cndmask_b32_e32 v68, v229, v68, vcc
	v_cmp_lt_u32_e32 vcc, s60, v117
	v_add_u32_e32 v117, 0xbfffffff, v116
	s_nop 0
	v_cndmask_b32_e32 v84, v229, v84, vcc
	v_cmp_lt_u32_e32 vcc, s60, v117
	v_add_u32_e32 v117, 0xbfffffdf, v116
	s_nop 0
	v_cndmask_b32_e32 v69, v229, v69, vcc
	v_cmp_lt_u32_e32 vcc, s60, v117
	v_add_u32_e32 v117, 0xbffffffe, v116
	s_nop 0
	v_cndmask_b32_e32 v85, v229, v85, vcc
	v_cmp_lt_u32_e32 vcc, s60, v117
	v_add_u32_e32 v117, 0xbfffffde, v116
	s_nop 0
	v_cndmask_b32_e32 v70, v229, v70, vcc
	v_cmp_lt_u32_e32 vcc, s60, v117
	v_add_u32_e32 v117, 0xbffffffd, v116
	s_nop 0
	v_cndmask_b32_e32 v86, v229, v86, vcc
	v_cmp_lt_u32_e32 vcc, s60, v117
	v_add_u32_e32 v117, 0xbfffffdd, v116
	s_nop 0
	v_cndmask_b32_e32 v71, v229, v71, vcc
	v_cmp_lt_u32_e32 vcc, s60, v117
	v_add_u32_e32 v117, 0xbffffff8, v116
	s_nop 0
	v_cndmask_b32_e32 v87, v229, v87, vcc
	v_cmp_lt_u32_e32 vcc, s60, v117
	v_add_u32_e32 v117, 0xbfffffd8, v116
	s_nop 0
	v_cndmask_b32_e32 v72, v229, v72, vcc
	v_cmp_lt_u32_e32 vcc, s60, v117
	v_add_u32_e32 v117, 0xbffffff7, v116
	s_nop 0
	v_cndmask_b32_e32 v88, v229, v88, vcc
	v_cmp_lt_u32_e32 vcc, s60, v117
	v_add_u32_e32 v117, 0xbfffffd7, v116
	s_nop 0
	v_cndmask_b32_e32 v73, v229, v73, vcc
	v_cmp_lt_u32_e32 vcc, s60, v117
	v_add_u32_e32 v117, 0xbffffff6, v116
	s_nop 0
	v_cndmask_b32_e32 v89, v229, v89, vcc
	v_cmp_lt_u32_e32 vcc, s60, v117
	v_add_u32_e32 v117, 0xbfffffd6, v116
	s_nop 0
	v_cndmask_b32_e32 v74, v229, v74, vcc
	v_cmp_lt_u32_e32 vcc, s60, v117
	v_add_u32_e32 v117, 0xbffffff5, v116
	s_nop 0
	v_cndmask_b32_e32 v90, v229, v90, vcc
	v_cmp_lt_u32_e32 vcc, s60, v117
	v_add_u32_e32 v117, 0xbfffffd5, v116
	s_nop 0
	v_cndmask_b32_e32 v75, v229, v75, vcc
	v_cmp_lt_u32_e32 vcc, s60, v117
	v_add_u32_e32 v117, 0xbffffff0, v116
	s_nop 0
	v_cndmask_b32_e32 v91, v229, v91, vcc
	v_cmp_lt_u32_e32 vcc, s60, v117
	v_add_u32_e32 v117, 0xbfffffd0, v116
	s_nop 0
	v_cndmask_b32_e32 v76, v229, v76, vcc
	v_cmp_lt_u32_e32 vcc, s60, v117
	v_add_u32_e32 v117, 0xbfffffef, v116
	s_nop 0
	v_cndmask_b32_e32 v92, v229, v92, vcc
	v_cmp_lt_u32_e32 vcc, s60, v117
	v_add_u32_e32 v117, 0xbfffffcf, v116
	s_nop 0
	v_cndmask_b32_e32 v77, v229, v77, vcc
	v_cmp_lt_u32_e32 vcc, s60, v117
	v_add_u32_e32 v117, 0xbfffffee, v116
	s_nop 0
	v_cndmask_b32_e32 v93, v229, v93, vcc
	v_cmp_lt_u32_e32 vcc, s60, v117
	v_add_u32_e32 v117, 0xbfffffce, v116
	s_nop 0
	v_cndmask_b32_e32 v78, v229, v78, vcc
	v_cmp_lt_u32_e32 vcc, s60, v117
	v_add_u32_e32 v117, 0xbfffffed, v116
	s_nop 0
	v_cndmask_b32_e32 v94, v229, v94, vcc
	v_cmp_lt_u32_e32 vcc, s60, v117
	v_add_u32_e32 v117, 0xbfffffcd, v116
	s_nop 0
	v_cndmask_b32_e32 v79, v229, v79, vcc
	v_cmp_lt_u32_e32 vcc, s60, v117
	v_add_u32_e32 v117, 0xbfffffe8, v116
	s_nop 0
	v_cndmask_b32_e32 v95, v229, v95, vcc
	v_cmp_lt_u32_e32 vcc, s60, v117
	v_add_u32_e32 v117, 0xbfffffc8, v116
	s_nop 0
	v_cndmask_b32_e32 v80, v229, v80, vcc
	v_cmp_lt_u32_e32 vcc, s60, v117
	v_add_u32_e32 v117, 0xbfffffe7, v116
	s_nop 0
	v_cndmask_b32_e32 v96, v229, v96, vcc
	v_cmp_lt_u32_e32 vcc, s60, v117
	v_add_u32_e32 v117, 0xbfffffc7, v116
	s_nop 0
	v_cndmask_b32_e32 v81, v229, v81, vcc
	v_cmp_lt_u32_e32 vcc, s60, v117
	v_add_u32_e32 v117, 0xbfffffe6, v116
	s_nop 0
	v_cndmask_b32_e32 v97, v229, v97, vcc
	v_cmp_lt_u32_e32 vcc, s60, v117
	v_add_u32_e32 v117, 0xbfffffc6, v116
	s_nop 0
	v_cndmask_b32_e32 v82, v229, v82, vcc
	v_cmp_lt_u32_e32 vcc, s60, v117
	v_add_u32_e32 v117, 0xbfffffe5, v116
	v_add_u32_e32 v116, 0xbfffffc5, v116
	v_cndmask_b32_e32 v98, v229, v98, vcc
	v_cmp_lt_u32_e32 vcc, s60, v117
	s_nop 1
	v_cndmask_b32_e32 v83, v229, v83, vcc
	v_cmp_lt_u32_e32 vcc, s60, v116
	s_nop 1
	v_cndmask_b32_e32 v99, v229, v99, vcc

; #define SBAR() __builtin_amdgcn_sched_barrier(0)
; #define RESC(a) do { if (__any((a) < 1.f)) { if (hi == 0) al_l[r32] = (a); asm volatile("s_waitcnt lgkmcnt(0)" ::: "memory");              \
;                      for (int d_ = 0; d_ < 4; ++d_) for (int r = 0; r < 16; ++r) o[d_][r] *= al_l[crow(r, hi)]; } } while (0)
; #define ACT(t) (KBASE(t) <= qlo + QBLK - 1 && KBASE(t) + KVBLK - 1 >= qlo - W + 1)
; #define MASKT(P0_, P1_, t) do { const int kb_ = KBASE(t); if ((!SK || ACT(t)) && (kb_ + KVBLK - 1 > qlo || kb_ <= qlo + QBLK - 1 - W)) mask_tile(P0_, P1_, qm - kb_, (unsigned)W); } while (0)
; __device__ __forceinline__ void partialSM(f32x16& p0, f32x16& p1, float& m_reg, float& mn, float& alpha) {
;     ...
;     const float mnL = -mn * C2;
;     for (int r = 0; r < 16; ++r) p0[r] = fmaf(p0[r], C2, mnL); for (int r = 0; r < 16; ++r) p1[r] = fmaf(p1[r], C2, mnL);
;     for (int r = 0; r < 16; ++r) p0[r] = __builtin_amdgcn_exp2f(p0[r]);
; }
; __device__ __forceinline__ void finishSM(f32x16& p0, f32x16& p1, float alpha, float& l_reg, bf16x8& pa0, bf16x8& pa1, bf16x8& pa2, bf16x8& pa3) {
;     for (int r = 0; r < 16; ++r) p1[r] = __builtin_amdgcn_exp2f(p1[r]);
;     float ps;
;     {
;       float s0 = p0[0] + p1[0], s1 = p0[1] + p1[1], s2 = p0[2] + p1[2], s3 = p0[3] + p1[3];
; #pragma unroll
;       for (int r = 4; r < 16; r += 4) { s0 += p0[r]; s1 += p0[r + 1]; s2 += p0[r + 2]; s3 += p0[r + 3]; s0 += p1[r]; s1 += p1[r + 1]; s2 += p1[r + 2]; s3 += p1[r + 3]; }
;       ps = (s0 + s1) + (s2 + s3); }
;     { auto rr = __builtin_amdgcn_permlane32_swap(__float_as_uint(ps), __float_as_uint(ps), false, false);
;       ps = __uint_as_float(rr[0]) + __uint_as_float(rr[1]); }
;     l_reg = l_reg * alpha + ps;
;     ...
;     PK4(p0, 0, pa0); PK4(p0, 8, pa1); PK4(p1, 0, pa2); PK4(p1, 8, pa3);
; __device__ __forceinline__ void block(const BlockRef& cur, const BlockRef& nxt, int skv, char* lds, Seam& S) {
;     ...
;     if (even) { MASKT(pB0, pB1, NT - 1); partialSM(pB0, pB1, m_reg, mnB, alB); __syncthreads(); RESC(alB);
;         finishSM(pB0, pB1, alB, l_reg, pa0, pa1, pa2, pa3); SBAR(); pv_tile<1, SK>(o, vb0, pa0, pa1, pa2, pa3, ACT(NT - 1)); }
.LBB0_410:
	v_cndmask_b32_e64 v117, v117, v188, s[6:7]
	v_mul_f32_e32 v117, 0xbe0293ee, v117
	v_fmamk_f32 v68, v68, 0x3e0293ee, v117
	v_fmamk_f32 v69, v69, 0x3e0293ee, v117
	v_fmamk_f32 v70, v70, 0x3e0293ee, v117
	v_fmamk_f32 v71, v71, 0x3e0293ee, v117
	v_fmamk_f32 v72, v72, 0x3e0293ee, v117
	v_fmamk_f32 v73, v73, 0x3e0293ee, v117
	v_fmamk_f32 v74, v74, 0x3e0293ee, v117
	v_fmamk_f32 v75, v75, 0x3e0293ee, v117
	v_fmamk_f32 v118, v76, 0x3e0293ee, v117
	v_fmamk_f32 v119, v77, 0x3e0293ee, v117
	v_fmamk_f32 v120, v78, 0x3e0293ee, v117
	v_fmamk_f32 v121, v79, 0x3e0293ee, v117
	v_fmamk_f32 v84, v84, 0x3e0293ee, v117
	v_fmamk_f32 v85, v85, 0x3e0293ee, v117
	v_fmamk_f32 v86, v86, 0x3e0293ee, v117
	v_fmamk_f32 v87, v87, 0x3e0293ee, v117
	v_fmamk_f32 v122, v80, 0x3e0293ee, v117
	v_fmamk_f32 v123, v81, 0x3e0293ee, v117
	v_fmamk_f32 v124, v82, 0x3e0293ee, v117
	v_fmamk_f32 v125, v83, 0x3e0293ee, v117
	v_exp_f32_e32 v81, v68
	v_exp_f32_e32 v83, v69
	v_exp_f32_e32 v80, v70
	v_exp_f32_e32 v82, v71
	v_exp_f32_e32 v77, v72
	v_exp_f32_e32 v79, v73
	v_exp_f32_e32 v76, v74
	v_exp_f32_e32 v78, v75
	v_exp_f32_e32 v73, v118
	v_exp_f32_e32 v75, v119
	v_exp_f32_e32 v72, v120
	v_exp_f32_e32 v74, v121
	v_exp_f32_e32 v119, v84
	v_exp_f32_e32 v121, v85
	v_exp_f32_e32 v118, v86
	v_exp_f32_e32 v120, v87
	v_fmamk_f32 v88, v88, 0x3e0293ee, v117
	v_fmamk_f32 v89, v89, 0x3e0293ee, v117
	v_fmamk_f32 v90, v90, 0x3e0293ee, v117
	v_fmamk_f32 v91, v91, 0x3e0293ee, v117
	v_exp_f32_e32 v69, v122
	v_exp_f32_e32 v71, v123
	v_exp_f32_e32 v123, v88
	v_exp_f32_e32 v89, v89
	v_exp_f32_e32 v122, v90
	v_exp_f32_e32 v88, v91
	v_fmamk_f32 v92, v92, 0x3e0293ee, v117
	v_fmamk_f32 v93, v93, 0x3e0293ee, v117
	v_fmamk_f32 v94, v94, 0x3e0293ee, v117
	v_fmamk_f32 v95, v95, 0x3e0293ee, v117
	v_exp_f32_e32 v91, v92
	v_exp_f32_e32 v93, v93
	v_exp_f32_e32 v90, v94
	v_exp_f32_e32 v92, v95
	v_pk_add_f32 v[84:85], v[80:81], v[118:119]
	v_pk_add_f32 v[86:87], v[82:83], v[120:121]
	v_fmamk_f32 v96, v96, 0x3e0293ee, v117
	v_exp_f32_e32 v68, v124
	v_exp_f32_e32 v70, v125
	v_fmamk_f32 v97, v97, 0x3e0293ee, v117
	v_fmamk_f32 v98, v98, 0x3e0293ee, v117
	v_fmac_f32_e32 v117, 0x3e0293ee, v99
	v_pk_add_f32 v[84:85], v[76:77], v[84:85]
	v_pk_add_f32 v[86:87], v[78:79], v[86:87]
	v_exp_f32_e32 v95, v96
	v_exp_f32_e32 v97, v97
	v_exp_f32_e32 v94, v98
	v_exp_f32_e32 v96, v117
	v_pk_add_f32 v[84:85], v[122:123], v[84:85]
	v_pk_add_f32 v[86:87], v[88:89], v[86:87]
	v_pk_add_f32 v[84:85], v[72:73], v[84:85]
	v_pk_add_f32 v[86:87], v[74:75], v[86:87]
	v_pk_add_f32 v[84:85], v[90:91], v[84:85]
	v_pk_add_f32 v[86:87], v[92:93], v[86:87]
	v_pk_add_f32 v[84:85], v[68:69], v[84:85]
	v_pk_add_f32 v[86:87], v[70:71], v[86:87]
	v_pk_add_f32 v[84:85], v[94:95], v[84:85]
	v_pk_add_f32 v[86:87], v[96:97], v[86:87]
	s_nop 0
	v_pk_add_f32 v[84:85], v[86:87], v[84:85]
	s_nop 0
	v_pk_add_f32 v[84:85], v[84:85], v[84:85] op_sel:[0,1] op_sel_hi:[1,0]
	s_nop 0
	v_mov_b32_e32 v85, v84
	s_nop 1
	v_permlane32_swap_b32_e32 v84, v85
	v_add_f32_e32 v124, v84, v85
	v_cvt_pk_bf16_f32 v84, v81, v83
	v_cvt_pk_bf16_f32 v85, v80, v82
	v_cvt_pk_bf16_f32 v86, v77, v79
	v_cvt_pk_bf16_f32 v87, v76, v78
	v_cvt_pk_bf16_f32 v76, v73, v75
	v_cvt_pk_bf16_f32 v77, v72, v74
	v_cvt_pk_bf16_f32 v78, v69, v71
	v_cvt_pk_bf16_f32 v79, v68, v70
	v_cvt_pk_bf16_f32 v68, v119, v121
	v_cvt_pk_bf16_f32 v69, v118, v120
	v_cvt_pk_bf16_f32 v70, v123, v89
	v_cvt_pk_bf16_f32 v71, v122, v88
	v_cvt_pk_bf16_f32 v72, v91, v93
	v_cvt_pk_bf16_f32 v73, v90, v92
	v_cvt_pk_bf16_f32 v74, v95, v97
	v_cvt_pk_bf16_f32 v75, v94, v96
	v_fmac_f32_e32 v124, v2, v116
	v_permlane32_swap_b32_e32 v84, v86
	v_permlane32_swap_b32_e32 v85, v87
	v_permlane32_swap_b32_e32 v76, v78
	v_permlane32_swap_b32_e32 v77, v79
	v_permlane32_swap_b32_e32 v68, v70
	v_permlane32_swap_b32_e32 v69, v71
	v_permlane32_swap_b32_e32 v72, v74
	v_permlane32_swap_b32_e32 v73, v75
	ds_read_b64_tr_b16 v[80:81], v221 offset:0x4000
	ds_read_b64_tr_b16 v[82:83], v221 offset:0x4800
	ds_read_b64_tr_b16 v[88:89], v221 offset:0x5000
	ds_read_b64_tr_b16 v[90:91], v221 offset:0x5800
	ds_read_b64_tr_b16 v[92:93], v221 offset:0x6000
	ds_read_b64_tr_b16 v[94:95], v221 offset:0x6800
	ds_read_b64_tr_b16 v[96:97], v221 offset:0x7000
	ds_read_b64_tr_b16 v[98:99], v221 offset:0x7800
	s_waitcnt lgkmcnt(0)
	s_nop 0
	v_mfma_f32_32x32x16_bf16 v[52:67], v[84:87], v[80:83], v[52:67]
	ds_read_b64_tr_b16 v[80:81], v221 offset:0x4200
	ds_read_b64_tr_b16 v[82:83], v221 offset:0x4a00
	v_mfma_f32_32x32x16_bf16 v[52:67], v[76:79], v[88:91], v[52:67]
	ds_read_b64_tr_b16 v[88:89], v221 offset:0x5200
	ds_read_b64_tr_b16 v[90:91], v221 offset:0x5a00
	v_mfma_f32_32x32x16_bf16 v[52:67], v[68:71], v[92:95], v[52:67]
	ds_read_b64_tr_b16 v[92:93], v221 offset:0x6200
	ds_read_b64_tr_b16 v[94:95], v221 offset:0x6a00
	ds_read_b64_tr_b16 v[116:117], v221 offset:0x7200
	ds_read_b64_tr_b16 v[118:119], v221 offset:0x7a00
	s_waitcnt lgkmcnt(0)
	v_mfma_f32_32x32x16_bf16 v[52:67], v[72:75], v[96:99], v[52:67]
	v_mfma_f32_32x32x16_bf16 v[36:51], v[84:87], v[80:83], v[36:51]
	ds_read_b64_tr_b16 v[80:81], v221 offset:0x4400
	ds_read_b64_tr_b16 v[82:83], v221 offset:0x4c00
	v_mfma_f32_32x32x16_bf16 v[36:51], v[76:79], v[88:91], v[36:51]
	ds_read_b64_tr_b16 v[88:89], v221 offset:0x5400
	ds_read_b64_tr_b16 v[90:91], v221 offset:0x5c00
	v_mfma_f32_32x32x16_bf16 v[36:51], v[68:71], v[92:95], v[36:51]
	ds_read_b64_tr_b16 v[92:93], v221 offset:0x6400
	ds_read_b64_tr_b16 v[94:95], v221 offset:0x6c00
	ds_read_b64_tr_b16 v[96:97], v221 offset:0x7400
	ds_read_b64_tr_b16 v[98:99], v221 offset:0x7c00
	s_waitcnt lgkmcnt(0)
	v_mfma_f32_32x32x16_bf16 v[36:51], v[72:75], v[116:119], v[36:51]
	v_mfma_f32_32x32x16_bf16 v[20:35], v[84:87], v[80:83], v[20:35]
	ds_read_b64_tr_b16 v[80:81], v221 offset:0x4600
	ds_read_b64_tr_b16 v[82:83], v221 offset:0x4e00
	v_mfma_f32_32x32x16_bf16 v[20:35], v[76:79], v[88:91], v[20:35]
	ds_read_b64_tr_b16 v[88:89], v221 offset:0x5600
	ds_read_b64_tr_b16 v[90:91], v221 offset:0x5e00
	v_mfma_f32_32x32x16_bf16 v[20:35], v[68:71], v[92:95], v[20:35]
	ds_read_b64_tr_b16 v[92:93], v221 offset:0x6600
	ds_read_b64_tr_b16 v[94:95], v221 offset:0x6e00
	ds_read_b64_tr_b16 v[116:117], v221 offset:0x7600
	ds_read_b64_tr_b16 v[118:119], v221 offset:0x7e00
	s_waitcnt lgkmcnt(0)
	v_mfma_f32_32x32x16_bf16 v[20:35], v[72:75], v[96:99], v[20:35]
	v_mfma_f32_32x32x16_bf16 v[4:19], v[84:87], v[80:83], v[4:19]
	v_mfma_f32_32x32x16_bf16 v[4:19], v[76:79], v[88:91], v[4:19]
	v_mfma_f32_32x32x16_bf16 v[4:19], v[68:71], v[92:95], v[4:19]
	v_mfma_f32_32x32x16_bf16 v[4:19], v[72:75], v[116:119], v[4:19]
	v_mov_b32_e32 v2, v124

; #define SEAM(k) do { if (IN(k) && IN((k) + 1)) { if (fast) xcd_barrier(xbar); else grid.sync(); } } while (0)
; __global__ void __launch_bounds__(512, 2) fwd_mega(Params P_by_kernarg) {
;     ...
;     SEAM(2);
.LBB0_543:
	s_setprio 0
	s_cmp_gt_i32 s65, 3
	s_cselect_b64 s[2:3], -1, 0
	s_and_b64 s[4:5], s[8:9], s[2:3]
	s_andn2_b64 vcc, exec, s[4:5]
	s_cbranch_vccnz .LBB0_607
	s_mov_b64 s[4:5], -1
	s_and_b64 vcc, exec, s[30:31]
	s_cbranch_vccz .LBB0_556
	s_waitcnt vmcnt(0)
	v_lshrrev_b32_e32 v2, 20, v0
	v_lshrrev_b32_e32 v3, 10, v0
	v_or_b32_e32 v2, v3, v2
	s_movk_i32 s4, 0x3ff
	v_and_or_b32 v2, v2, s4, v1
	v_cmp_eq_u32_e32 vcc, 0, v2
	s_waitcnt lgkmcnt(0)
	s_barrier
	s_and_saveexec_b64 s[4:5], vcc
	s_cbranch_execz .LBB0_555
	buffer_wbl2 sc1
	s_load_dwordx2 s[6:7], s[28:29], 0x58
	v_mov_b32_e32 v4, 0
	s_mov_b64 s[8:9], exec
	v_mbcnt_lo_u32_b32 v3, s8, 0
	v_mbcnt_hi_u32_b32 v3, s9, v3
	s_waitcnt lgkmcnt(0)
	global_load_dword v2, v4, s[6:7] offset:40
	v_cmp_eq_u32_e32 vcc, 0, v3
	s_and_saveexec_b64 s[10:11], vcc
	s_cbranch_execz .LBB0_548
	s_bcnt1_i32_b64 s8, s[8:9]
	v_mov_b32_e32 v5, s8
	global_atomic_add v5, v4, v5, s[6:7] offset:32 sc0
